# code layout: attention slow-path and rescale blocks moved out of line so the fast path falls through (2 fewer taken branches per tile)
# speedup vs baseline: 1.0025x; 1.0025x over previous
; __device__ __forceinline__ void finishSM(f32x16& p0, f32x16& p1, float alpha, float& l_reg, bf16x8& pa0, bf16x8& pa1, bf16x8& pa2, bf16x8& pa3) {
; #pragma unroll
;   for (int r = 0; r < 16; ++r) p1[r] = __builtin_amdgcn_exp2f(p1[r]);
;   float ps = 0;
; #pragma unroll
;   for (int r = 0; r < 16; ++r) ps += p0[r];
; #pragma unroll
;   for (int r = 0; r < 16; ++r) ps += p1[r];
;   { auto rr = __builtin_amdgcn_permlane32_swap(__float_as_uint(ps), __float_as_uint(ps), false, false);
;     ps = __uint_as_float(rr[0]) + __uint_as_float(rr[1]); }
;   l_reg = l_reg * alpha + ps;
;     ...
;   PK4(p0, 0, pa0); PK4(p0, 8, pa1); PK4(p1, 0, pa2); PK4(p1, 8, pa3);
;     ...
; }
; template <int DQK> __device__ __forceinline__ void qkt(f32x16& p0, f32x16& p1, const char* Ks, const bf16x8* qr, int r32, int hi, const f32x16& negm) {
; #pragma unroll
;   for (int d0 = 0; d0 < DQK / 16; ++d0) { const int cb = (d0 * 16 + hi * 8) * 2;
;     const bf16x8 b0 = *reinterpret_cast<const bf16x8*>(Ks + (DQK == 128 ? KSWZ(r32, cb) : KSWZ64(r32, cb)));
;     const bf16x8 b1 = *reinterpret_cast<const bf16x8*>(Ks + (DQK == 128 ? KSWZ(32 + r32, cb) : KSWZ64(32 + r32, cb)));
;     if (d0 == 0) { p0 = __builtin_amdgcn_mfma_f32_32x32x16_bf16(b0, qr[0], negm, 0, 0, 0); p1 = __builtin_amdgcn_mfma_f32_32x32x16_bf16(b1, qr[0], negm, 0, 0, 0); }
;     else { p0 = __builtin_amdgcn_mfma_f32_32x32x16_bf16(b0, qr[d0], p0, 0, 0, 0); p1 = __builtin_amdgcn_mfma_f32_32x32x16_bf16(b1, qr[d0], p1, 0, 0, 0); } }
; }
; __device__ __forceinline__ int v_st(int k, int c) { const int kk = (k & ~0xC) | ((k & 4) << 1) | ((k & 8) >> 1); return ((kk >> 3) * 4 + (c >> 5)) * 512 + ((kk & 7) * 32 + (c & 31)) * 2; }
; __device__ __forceinline__ int v_rd_base(int lane) { return ((lane & 3) << 3) | (((lane >> 2) & 3) << 6) | (((lane >> 4) & 1) << 5) | (((lane >> 5) & 1) << 8); }
; template <int OFF> __device__ __forceinline__ s16x4 tr_read(int vb) {
;   s16x4 r; asm volatile("ds_read_b64_tr_b16 %0, %1 offset:%2" : "=&v"(r) : "v"(vb), "i"(OFF) : "memory"); return r;
; }
; template <int D0> __device__ __forceinline__ void pv_one(f32x16& od, int vb, bf16x8 pa0, bf16x8 pa1, bf16x8 pa2, bf16x8 pa3) {
;   const s16x4 l0 = tr_read<v_rd_off(D0, 0, 0)>(vb), h0 = tr_read<v_rd_off(D0, 0, 1)>(vb), l1 = tr_read<v_rd_off(D0, 1, 0)>(vb), h1 = tr_read<v_rd_off(D0, 1, 1)>(vb);
.LBB0_69:
	s_add_i32 s99, s12, 64
	s_cmp_le_u32 s99, s16
	s_cbranch_scc0 .Lslow_g1
	ds_read_b128 v[198:201], v195 offset:57344
	ds_read_b128 v[202:205], v195 offset:49152
	ds_read_b128 v[244:247], v211 offset:57344
	ds_read_b128 v[206:209], v211 offset:49152
	v_add_f32_e32 v227, 0, v238
	v_add_f32_e32 v227, v240, v227
	v_cvt_pk_bf16_f32 v66, v238, v240
	v_add_f32_e32 v227, v236, v227
	v_add_f32_e32 v227, v239, v227
	v_cvt_pk_bf16_f32 v67, v236, v239
	v_add_f32_e32 v227, v235, v227
	v_add_f32_e32 v227, v237, v227
	v_cvt_pk_bf16_f32 v68, v235, v237
	v_add_f32_e32 v227, v233, v227
	v_add_f32_e32 v227, v234, v227
	v_cvt_pk_bf16_f32 v69, v233, v234
	s_waitcnt lgkmcnt(3)
	v_mfma_f32_32x32x16_bf16 v[114:129], v[198:201], v[174:177], v[82:97]
	v_add_f32_e32 v227, v184, v227
	v_add_f32_e32 v227, v232, v227
	v_cvt_pk_bf16_f32 v70, v184, v232
	v_add_f32_e32 v227, v183, v227
	v_add_f32_e32 v227, v185, v227
	s_waitcnt lgkmcnt(2)
	v_mfma_f32_32x32x16_bf16 v[130:145], v[202:205], v[174:177], v[82:97]
	ds_read_b128 v[198:201], v210 offset:57344
	ds_read_b128 v[202:205], v210 offset:49152
	v_cvt_pk_bf16_f32 v71, v183, v185
	v_add_f32_e32 v227, v180, v227
	v_add_f32_e32 v227, v182, v227
	v_cvt_pk_bf16_f32 v72, v180, v182
	v_add_f32_e32 v227, v179, v227
	s_waitcnt lgkmcnt(3)
	v_mfma_f32_32x32x16_bf16 v[114:129], v[244:247], v[170:173], v[114:129]
	v_add_f32_e32 v227, v181, v227
	v_cvt_pk_bf16_f32 v73, v179, v181
	v_exp_f32_e32 v98, v98
	v_exp_f32_e32 v99, v99
	v_permlane32_swap_b32_e32 v66, v68
	s_waitcnt lgkmcnt(2)
	v_mfma_f32_32x32x16_bf16 v[130:145], v[206:209], v[170:173], v[130:145]
	ds_read_b128 v[244:247], v197 offset:57344
	ds_read_b128 v[206:209], v197 offset:49152
	v_permlane32_swap_b32_e32 v67, v69
	v_permlane32_swap_b32_e32 v70, v72
	v_permlane32_swap_b32_e32 v71, v73
	v_exp_f32_e32 v100, v100
	v_add_f32_e32 v227, v98, v227
	s_waitcnt lgkmcnt(3)
	v_mfma_f32_32x32x16_bf16 v[114:129], v[198:201], v[166:169], v[114:129]
	v_exp_f32_e32 v101, v101
	v_add_f32_e32 v227, v99, v227
	v_exp_f32_e32 v102, v102
	v_add_f32_e32 v227, v100, v227
	v_exp_f32_e32 v103, v103
	s_waitcnt lgkmcnt(2)
	v_mfma_f32_32x32x16_bf16 v[130:145], v[202:205], v[166:169], v[130:145]
	ds_read_b128 v[198:201], v196 offset:57344
	ds_read_b128 v[202:205], v196 offset:49152
	v_add_f32_e32 v227, v101, v227
	v_exp_f32_e32 v104, v104
	v_add_f32_e32 v227, v102, v227
	v_exp_f32_e32 v105, v105
	s_waitcnt lgkmcnt(3)
	v_mfma_f32_32x32x16_bf16 v[114:129], v[244:247], v[162:165], v[114:129]
	v_add_f32_e32 v227, v103, v227
	v_exp_f32_e32 v106, v106
	v_add_f32_e32 v227, v104, v227
	v_exp_f32_e32 v107, v107
	s_waitcnt lgkmcnt(2)
	v_mfma_f32_32x32x16_bf16 v[130:145], v[206:209], v[162:165], v[130:145]
	ds_read_b128 v[244:247], v222 offset:57344
	ds_read_b128 v[206:209], v222 offset:49152
	v_add_f32_e32 v227, v105, v227
	v_exp_f32_e32 v108, v108
	v_add_f32_e32 v227, v106, v227
	v_exp_f32_e32 v109, v109
	s_waitcnt lgkmcnt(3)
	v_mfma_f32_32x32x16_bf16 v[114:129], v[198:201], v[158:161], v[114:129]
	v_add_f32_e32 v227, v107, v227
	v_exp_f32_e32 v110, v110
	v_add_f32_e32 v227, v108, v227
	v_exp_f32_e32 v111, v111
	s_waitcnt lgkmcnt(2)
	v_mfma_f32_32x32x16_bf16 v[130:145], v[202:205], v[158:161], v[130:145]
	ds_read_b128 v[198:201], v223 offset:57344
	ds_read_b128 v[202:205], v223 offset:49152
	v_add_f32_e32 v227, v109, v227
	v_exp_f32_e32 v112, v112
	v_add_f32_e32 v227, v110, v227
	v_exp_f32_e32 v113, v113
	s_waitcnt lgkmcnt(3)
	v_mfma_f32_32x32x16_bf16 v[114:129], v[244:247], v[154:157], v[114:129]
	v_add_f32_e32 v227, v111, v227
	v_add_f32_e32 v227, v112, v227
	v_add_f32_e32 v227, v113, v227
	v_mov_b32_e32 v228, v227
	s_waitcnt lgkmcnt(2)
	v_mfma_f32_32x32x16_bf16 v[130:145], v[206:209], v[154:157], v[130:145]
	ds_read_b128 v[244:247], v224 offset:57344
	ds_read_b128 v[206:209], v224 offset:49152
	v_cvt_pk_bf16_f32 v74, v98, v99
	v_cvt_pk_bf16_f32 v75, v100, v101
	v_cvt_pk_bf16_f32 v76, v102, v103
	v_cvt_pk_bf16_f32 v77, v104, v105
	s_waitcnt lgkmcnt(3)
	v_mfma_f32_32x32x16_bf16 v[114:129], v[198:201], v[150:153], v[114:129]
	v_cvt_pk_bf16_f32 v78, v106, v107
	v_cvt_pk_bf16_f32 v79, v108, v109
	v_cvt_pk_bf16_f32 v80, v110, v111
	v_cvt_pk_bf16_f32 v81, v112, v113
	s_waitcnt lgkmcnt(2)
	v_mfma_f32_32x32x16_bf16 v[130:145], v[202:205], v[150:153], v[130:145]
	ds_read_b64_tr_b16 v[178:179], v193 offset:0
	ds_read_b64_tr_b16 v[180:181], v193 offset:0x800
	ds_read_b64_tr_b16 v[182:183], v193 offset:0x200
	ds_read_b64_tr_b16 v[184:185], v193 offset:0xa00
	ds_read_b64_tr_b16 v[198:199], v193 offset:0x400
	ds_read_b64_tr_b16 v[200:201], v193 offset:0xc00
	ds_read_b64_tr_b16 v[202:203], v193 offset:0x600
	ds_read_b64_tr_b16 v[204:205], v193 offset:0xe00
	v_permlane32_swap_b32_e32 v227, v228
	v_permlane32_swap_b32_e32 v74, v76
	v_permlane32_swap_b32_e32 v75, v77
	v_permlane32_swap_b32_e32 v78, v80
	s_waitcnt lgkmcnt(9)
	v_mfma_f32_32x32x16_bf16 v[114:129], v[244:247], v[146:149], v[114:129]
	v_permlane32_swap_b32_e32 v79, v81
	v_add_co_u32_e32 v218, vcc, s77, v186
	s_nop 1
	v_addc_co_u32_e32 v219, vcc, 0, v187, vcc
	s_waitcnt lgkmcnt(8)
	v_mfma_f32_32x32x16_bf16 v[130:145], v[206:209], v[146:149], v[130:145]
	global_load_dwordx4 v[98:101], v[186:187], off offset:512
	global_load_dwordx4 v[102:105], v[186:187], off
	global_load_dwordx4 v[110:113], v[218:219], off offset:512
	global_load_dwordx4 v[106:109], v[218:219], off
	s_waitcnt lgkmcnt(6)
	v_mfma_f32_32x32x16_bf16 v[2:17], v[66:69], v[178:181], v[2:17]
	ds_read_b64_tr_b16 v[178:179], v193 offset:0x1000
	ds_read_b64_tr_b16 v[180:181], v193 offset:0x1800
	s_waitcnt lgkmcnt(6)
; #define SBAR() __builtin_amdgcn_sched_barrier(0)
; template <int OFF> __device__ __forceinline__ s16x4 tr_read(int vb) {
;   s16x4 r; asm volatile("ds_read_b64_tr_b16 %0, %1 offset:%2" : "=&v"(r) : "v"(vb), "i"(OFF) : "memory"); return r;
; }
; template <int D0> __device__ __forceinline__ void pv_one(f32x16& od, int vb, bf16x8 pa0, bf16x8 pa1, bf16x8 pa2, bf16x8 pa3) {
;   const s16x4 l0 = tr_read<v_rd_off(D0, 0, 0)>(vb), h0 = tr_read<v_rd_off(D0, 0, 1)>(vb), l1 = tr_read<v_rd_off(D0, 1, 0)>(vb), h1 = tr_read<v_rd_off(D0, 1, 1)>(vb);
;   const s16x4 l2 = tr_read<v_rd_off(D0, 2, 0)>(vb), h2 = tr_read<v_rd_off(D0, 2, 1)>(vb), l3 = tr_read<v_rd_off(D0, 3, 0)>(vb), h3 = tr_read<v_rd_off(D0, 3, 1)>(vb);
;   asm volatile("s_waitcnt lgkmcnt(0)" ::: "memory"); SBAR();
;     ...
;   od = __builtin_amdgcn_mfma_f32_32x32x16_bf16(pa0, PK(l0, h0), od, 0, 0, 0);
;   od = __builtin_amdgcn_mfma_f32_32x32x16_bf16(pa1, PK(l1, h1), od, 0, 0, 0);
;   od = __builtin_amdgcn_mfma_f32_32x32x16_bf16(pa2, PK(l2, h2), od, 0, 0, 0);
;   od = __builtin_amdgcn_mfma_f32_32x32x16_bf16(pa3, PK(l3, h3), od, 0, 0, 0);
;     ...
; }
; __device__ __forceinline__ void pv_d0(f32x16* o, int vb, bf16x8 pa0, bf16x8 pa1, bf16x8 pa2, bf16x8 pa3) {
;   pv_one<0>(o[0], vb, pa0, pa1, pa2, pa3); pv_one<1>(o[1], vb, pa0, pa1, pa2, pa3); pv_one<2>(o[2], vb, pa0, pa1, pa2, pa3); pv_one<3>(o[3], vb, pa0, pa1, pa2, pa3);
; }
	v_mfma_f32_32x32x16_bf16 v[50:65], v[66:69], v[182:185], v[50:65]
	ds_read_b64_tr_b16 v[182:183], v193 offset:0x1200
	ds_read_b64_tr_b16 v[184:185], v193 offset:0x1a00
	s_waitcnt lgkmcnt(6)
	v_mfma_f32_32x32x16_bf16 v[34:49], v[66:69], v[198:201], v[34:49]
	ds_read_b64_tr_b16 v[198:199], v193 offset:0x1400
	ds_read_b64_tr_b16 v[200:201], v193 offset:0x1c00
	s_waitcnt lgkmcnt(6)
	v_mfma_f32_32x32x16_bf16 v[18:33], v[66:69], v[202:205], v[18:33]
	ds_read_b64_tr_b16 v[202:203], v193 offset:0x1600
	ds_read_b64_tr_b16 v[204:205], v193 offset:0x1e00
	s_waitcnt lgkmcnt(6)
	v_mfma_f32_32x32x16_bf16 v[2:17], v[70:73], v[178:181], v[2:17]
	ds_read_b64_tr_b16 v[178:179], v193 offset:0x2000
	ds_read_b64_tr_b16 v[180:181], v193 offset:0x2800
	v_max_f32_e32 v218, v130, v131
	v_max3_f32 v218, v218, v132, v133
	s_waitcnt lgkmcnt(6)
	v_mfma_f32_32x32x16_bf16 v[50:65], v[70:73], v[182:185], v[50:65]
	ds_read_b64_tr_b16 v[182:183], v193 offset:0x2200
	ds_read_b64_tr_b16 v[184:185], v193 offset:0x2a00
	v_max3_f32 v218, v218, v134, v135
	v_max3_f32 v218, v218, v136, v137
	s_waitcnt lgkmcnt(6)
	v_mfma_f32_32x32x16_bf16 v[34:49], v[70:73], v[198:201], v[34:49]
	ds_read_b64_tr_b16 v[198:199], v193 offset:0x2400
	ds_read_b64_tr_b16 v[200:201], v193 offset:0x2c00
	v_max3_f32 v218, v218, v138, v139
	v_max3_f32 v218, v218, v140, v141
	s_waitcnt lgkmcnt(6)
	v_mfma_f32_32x32x16_bf16 v[18:33], v[70:73], v[202:205], v[18:33]
	ds_read_b64_tr_b16 v[202:203], v193 offset:0x2600
	ds_read_b64_tr_b16 v[204:205], v193 offset:0x2e00
	v_max3_f32 v218, v218, v142, v143
	v_max3_f32 v218, v218, v144, v145
	s_waitcnt lgkmcnt(6)
	v_mfma_f32_32x32x16_bf16 v[2:17], v[74:77], v[178:181], v[2:17]
	ds_read_b64_tr_b16 v[178:179], v193 offset:0x3000
	ds_read_b64_tr_b16 v[180:181], v193 offset:0x3800
	v_max3_f32 v218, v218, v114, v115
	v_max3_f32 v218, v218, v116, v117
	s_waitcnt lgkmcnt(6)
	v_mfma_f32_32x32x16_bf16 v[50:65], v[74:77], v[182:185], v[50:65]
	ds_read_b64_tr_b16 v[182:183], v193 offset:0x3200
	ds_read_b64_tr_b16 v[184:185], v193 offset:0x3a00
	v_max3_f32 v218, v218, v118, v119
	v_max3_f32 v218, v218, v120, v121
	s_waitcnt lgkmcnt(6)
	v_mfma_f32_32x32x16_bf16 v[34:49], v[74:77], v[198:201], v[34:49]
	ds_read_b64_tr_b16 v[198:199], v193 offset:0x3400
	ds_read_b64_tr_b16 v[200:201], v193 offset:0x3c00
	v_max3_f32 v218, v218, v122, v123
	s_waitcnt lgkmcnt(6)
	v_mfma_f32_32x32x16_bf16 v[18:33], v[74:77], v[202:205], v[18:33]
	ds_read_b64_tr_b16 v[202:203], v193 offset:0x3600
	ds_read_b64_tr_b16 v[204:205], v193 offset:0x3e00
	v_max3_f32 v218, v218, v124, v125
	s_waitcnt lgkmcnt(6)
	v_mfma_f32_32x32x16_bf16 v[2:17], v[78:81], v[178:181], v[2:17]
	v_max3_f32 v218, v218, v126, v127
	s_waitcnt lgkmcnt(4)
	v_mfma_f32_32x32x16_bf16 v[50:65], v[78:81], v[182:185], v[50:65]
	v_max3_f32 v218, v218, v128, v129
	s_waitcnt lgkmcnt(2)
	v_mfma_f32_32x32x16_bf16 v[34:49], v[78:81], v[198:201], v[34:49]
	v_mov_b32_e32 v219, v218
	s_waitcnt lgkmcnt(0)
	v_mfma_f32_32x32x16_bf16 v[18:33], v[78:81], v[202:205], v[18:33]
	v_permlane32_swap_b32_e32 v218, v219
	v_max_f32_e32 v66, v218, v219
.Ljoin_g1:
	v_cmp_ge_f32_e32 vcc, s30, v66
	s_cmp_eq_u64 vcc, exec
	s_cbranch_scc0 .LBB0_87
	v_mov_b32_e32 v229, 1.0
.LBB0_72:
	s_barrier
	s_waitcnt vmcnt(0)
	v_cmp_gt_f32_e32 vcc, 1.0, v229
	s_waitcnt vmcnt(3)
	ds_write_b128 v191, v[98:101]
	s_waitcnt vmcnt(1)
	ds_write_b128 v192, v[110:113]
	ds_write_b128 v212, v[102:105] offset:32768
	s_waitcnt vmcnt(0)
	ds_write_b128 v213, v[106:109] offset:32768
	s_cbranch_vccnz .Lresc_g1
.LBB0_76:
	s_add_i32 s14, s12, 0x80
	v_exp_f32_e32 v178, v130
	v_exp_f32_e32 v205, v131
	v_exp_f32_e32 v179, v132
	v_exp_f32_e32 v204, v133
	v_exp_f32_e32 v180, v134
	v_exp_f32_e32 v203, v135
	v_exp_f32_e32 v181, v136
	v_exp_f32_e32 v202, v137
	v_exp_f32_e32 v182, v138
	v_exp_f32_e32 v201, v139
	v_exp_f32_e32 v183, v140
	v_exp_f32_e32 v200, v141
	v_exp_f32_e32 v184, v142
	v_exp_f32_e32 v199, v143
	v_exp_f32_e32 v185, v144
	v_exp_f32_e32 v198, v145
	s_waitcnt lgkmcnt(0)
	s_barrier
	s_cmp_le_u32 s14, s16
	s_cbranch_scc0 .Lslow_g2
	ds_read_b128 v[232:235], v195 offset:40960
	ds_read_b128 v[236:239], v195 offset:32768
	ds_read_b128 v[244:247], v211 offset:40960
	ds_read_b128 v[240:243], v211 offset:32768
	v_add_f32_e32 v230, 0, v178
	v_add_f32_e32 v230, v205, v230
	v_cvt_pk_bf16_f32 v178, v178, v205
	v_add_f32_e32 v230, v179, v230
	v_add_f32_e32 v230, v204, v230
	v_cvt_pk_bf16_f32 v179, v179, v204
	v_add_f32_e32 v230, v180, v230
	v_add_f32_e32 v230, v203, v230
	v_cvt_pk_bf16_f32 v180, v180, v203
	v_add_f32_e32 v230, v181, v230
	v_add_f32_e32 v230, v202, v230
	v_cvt_pk_bf16_f32 v181, v181, v202
	s_waitcnt lgkmcnt(3)
	v_mfma_f32_32x32x16_bf16 v[98:113], v[232:235], v[174:177], v[82:97]
	v_add_f32_e32 v230, v182, v230
	v_add_f32_e32 v230, v201, v230
	v_cvt_pk_bf16_f32 v182, v182, v201
	v_add_f32_e32 v230, v183, v230
	v_add_f32_e32 v230, v200, v230
	s_waitcnt lgkmcnt(2)
	v_mfma_f32_32x32x16_bf16 v[130:145], v[236:239], v[174:177], v[82:97]
	ds_read_b128 v[232:235], v210 offset:40960
	ds_read_b128 v[236:239], v210 offset:32768
	v_cvt_pk_bf16_f32 v183, v183, v200
	v_add_f32_e32 v230, v184, v230
	v_add_f32_e32 v230, v199, v230
	v_cvt_pk_bf16_f32 v184, v184, v199
	v_add_f32_e32 v230, v185, v230
	s_waitcnt lgkmcnt(3)
	v_mfma_f32_32x32x16_bf16 v[98:113], v[244:247], v[170:173], v[98:113]
	v_add_f32_e32 v230, v198, v230
	v_cvt_pk_bf16_f32 v185, v185, v198
	v_exp_f32_e32 v114, v114
	v_exp_f32_e32 v115, v115
	v_permlane32_swap_b32_e32 v178, v180
	s_waitcnt lgkmcnt(2)
; #define SBAR() __builtin_amdgcn_sched_barrier(0)
; #define SLOAD(i, k0) do { sr_[i].vs0 = GLD8(&Vh[(long)((k0) + sr) * LD + sc]); sr_[i].vs1 = GLD8(&Vh[(long)((k0) + 32 + sr) * LD + sc]); \
;     if (DQK == 128) { sr_[i].ks0 = GLD8(&Kh[(long)((k0) + sr) * LD + sc]); sr_[i].ks1 = GLD8(&Kh[(long)((k0) + 32 + sr) * LD + sc]); } \
;     else { sr_[i].ks0 = GLD8(&Kh[(long)((k0) + kr) * LD + kc]); } } while (0)
; __device__ __forceinline__ void finishSM(f32x16& p0, f32x16& p1, float alpha, float& l_reg, bf16x8& pa0, bf16x8& pa1, bf16x8& pa2, bf16x8& pa3) {
; #pragma unroll
;   for (int r = 0; r < 16; ++r) p1[r] = __builtin_amdgcn_exp2f(p1[r]);
;   float ps = 0;
; #pragma unroll
;   for (int r = 0; r < 16; ++r) ps += p0[r];
; #pragma unroll
;   for (int r = 0; r < 16; ++r) ps += p1[r];
;   { auto rr = __builtin_amdgcn_permlane32_swap(__float_as_uint(ps), __float_as_uint(ps), false, false);
;     ps = __uint_as_float(rr[0]) + __uint_as_float(rr[1]); }
;   l_reg = l_reg * alpha + ps;
;     ...
;   PK4(p0, 0, pa0); PK4(p0, 8, pa1); PK4(p1, 0, pa2); PK4(p1, 8, pa3);
;     ...
; }
; template <int DQK> __device__ __forceinline__ void qkt(f32x16& p0, f32x16& p1, const char* Ks, const bf16x8* qr, int r32, int hi, const f32x16& negm) {
; #pragma unroll
;   for (int d0 = 0; d0 < DQK / 16; ++d0) { const int cb = (d0 * 16 + hi * 8) * 2;
;     const bf16x8 b0 = *reinterpret_cast<const bf16x8*>(Ks + (DQK == 128 ? KSWZ(r32, cb) : KSWZ64(r32, cb)));
;     const bf16x8 b1 = *reinterpret_cast<const bf16x8*>(Ks + (DQK == 128 ? KSWZ(32 + r32, cb) : KSWZ64(32 + r32, cb)));
;     if (d0 == 0) { p0 = __builtin_amdgcn_mfma_f32_32x32x16_bf16(b0, qr[0], negm, 0, 0, 0); p1 = __builtin_amdgcn_mfma_f32_32x32x16_bf16(b1, qr[0], negm, 0, 0, 0); }
;     else { p0 = __builtin_amdgcn_mfma_f32_32x32x16_bf16(b0, qr[d0], p0, 0, 0, 0); p1 = __builtin_amdgcn_mfma_f32_32x32x16_bf16(b1, qr[d0], p1, 0, 0, 0); } }
; }
; template <int DQK, bool BIAS, bool VIRT = false>
; __device__ __forceinline__ void attn_pass(const bf16_t* __restrict__ Qb, const bf16_t* __restrict__ Kh, const bf16_t* __restrict__ Vh, int L, int NT, int qw0, const float* lut, f32x16 (&o)[4], char* lds, int nact) {
;     ...
;     NEGM(j + 1); SBAR(); qkt<DQK>(pA0, pA1, K_lds, qr, r32, hi, negm);
;     finishSM(pB0, pB1, alB, l_reg, pa0, pa1, pa2, pa3); SBAR();
;     if (SDEPTH == 1 || j + 3 < NT) SLOAD(SE, (j + 1 + SDEPTH) * KVBLK); SBAR();
	v_mfma_f32_32x32x16_bf16 v[130:145], v[240:243], v[170:173], v[130:145]
	ds_read_b128 v[244:247], v197 offset:40960
	ds_read_b128 v[240:243], v197 offset:32768
	v_permlane32_swap_b32_e32 v179, v181
	v_permlane32_swap_b32_e32 v182, v184
	v_permlane32_swap_b32_e32 v183, v185
	v_exp_f32_e32 v116, v116
	v_add_f32_e32 v230, v114, v230
	s_waitcnt lgkmcnt(3)
	v_mfma_f32_32x32x16_bf16 v[98:113], v[232:235], v[166:169], v[98:113]
	v_exp_f32_e32 v117, v117
	v_add_f32_e32 v230, v115, v230
	v_exp_f32_e32 v118, v118
	v_add_f32_e32 v230, v116, v230
	v_exp_f32_e32 v119, v119
	s_waitcnt lgkmcnt(2)
	v_mfma_f32_32x32x16_bf16 v[130:145], v[236:239], v[166:169], v[130:145]
	ds_read_b128 v[232:235], v196 offset:40960
	ds_read_b128 v[236:239], v196 offset:32768
	v_add_f32_e32 v230, v117, v230
	v_exp_f32_e32 v120, v120
	v_add_f32_e32 v230, v118, v230
	v_exp_f32_e32 v121, v121
	s_waitcnt lgkmcnt(3)
	v_mfma_f32_32x32x16_bf16 v[98:113], v[244:247], v[162:165], v[98:113]
	v_add_f32_e32 v230, v119, v230
	v_exp_f32_e32 v122, v122
	v_add_f32_e32 v230, v120, v230
	v_exp_f32_e32 v123, v123
	s_waitcnt lgkmcnt(2)
	v_mfma_f32_32x32x16_bf16 v[130:145], v[240:243], v[162:165], v[130:145]
	ds_read_b128 v[244:247], v222 offset:40960
	ds_read_b128 v[240:243], v222 offset:32768
	v_add_f32_e32 v230, v121, v230
	v_exp_f32_e32 v124, v124
	v_add_f32_e32 v230, v122, v230
	v_exp_f32_e32 v125, v125
	s_waitcnt lgkmcnt(3)
	v_mfma_f32_32x32x16_bf16 v[98:113], v[232:235], v[158:161], v[98:113]
	v_add_f32_e32 v230, v123, v230
	v_exp_f32_e32 v126, v126
	v_add_f32_e32 v230, v124, v230
	v_exp_f32_e32 v127, v127
	s_waitcnt lgkmcnt(2)
	v_mfma_f32_32x32x16_bf16 v[130:145], v[236:239], v[158:161], v[130:145]
	ds_read_b128 v[232:235], v223 offset:40960
	ds_read_b128 v[236:239], v223 offset:32768
	v_add_f32_e32 v230, v125, v230
	v_exp_f32_e32 v128, v128
	v_add_f32_e32 v230, v126, v230
	v_exp_f32_e32 v129, v129
	s_waitcnt lgkmcnt(3)
	v_mfma_f32_32x32x16_bf16 v[98:113], v[244:247], v[154:157], v[98:113]
	v_add_f32_e32 v230, v127, v230
	v_add_f32_e32 v230, v128, v230
	v_add_f32_e32 v230, v129, v230
	v_mov_b32_e32 v231, v230
	s_waitcnt lgkmcnt(2)
	v_mfma_f32_32x32x16_bf16 v[130:145], v[240:243], v[154:157], v[130:145]
	ds_read_b128 v[244:247], v224 offset:40960
	ds_read_b128 v[240:243], v224 offset:32768
	v_cvt_pk_bf16_f32 v198, v114, v115
	v_cvt_pk_bf16_f32 v199, v116, v117
	v_cvt_pk_bf16_f32 v200, v118, v119
	v_cvt_pk_bf16_f32 v201, v120, v121
	s_waitcnt lgkmcnt(3)
	v_mfma_f32_32x32x16_bf16 v[98:113], v[232:235], v[150:153], v[98:113]
	v_cvt_pk_bf16_f32 v202, v122, v123
	v_cvt_pk_bf16_f32 v203, v124, v125
	v_cvt_pk_bf16_f32 v204, v126, v127
	v_cvt_pk_bf16_f32 v205, v128, v129
	s_waitcnt lgkmcnt(2)
	v_mfma_f32_32x32x16_bf16 v[130:145], v[236:239], v[150:153], v[130:145]
	ds_read_b64_tr_b16 v[206:207], v190 offset:0
	ds_read_b64_tr_b16 v[208:209], v190 offset:0x800
	ds_read_b64_tr_b16 v[232:233], v190 offset:0x200
	ds_read_b64_tr_b16 v[234:235], v190 offset:0xa00
	ds_read_b64_tr_b16 v[236:237], v190 offset:0x400
	ds_read_b64_tr_b16 v[238:239], v190 offset:0xc00
	v_permlane32_swap_b32_e32 v230, v231
	v_permlane32_swap_b32_e32 v198, v200
	v_permlane32_swap_b32_e32 v199, v201
	v_permlane32_swap_b32_e32 v202, v204
	s_waitcnt lgkmcnt(7)
	v_mfma_f32_32x32x16_bf16 v[98:113], v[244:247], v[146:149], v[98:113]
	v_permlane32_swap_b32_e32 v203, v205
	v_add_co_u32_e32 v218, vcc, s80, v186
	s_nop 1
	v_addc_co_u32_e32 v219, vcc, 0, v187, vcc
	s_waitcnt lgkmcnt(6)
	v_mfma_f32_32x32x16_bf16 v[130:145], v[240:243], v[146:149], v[130:145]
	ds_read_b64_tr_b16 v[240:241], v190 offset:0x600
	ds_read_b64_tr_b16 v[242:243], v190 offset:0xe00
	global_load_dwordx4 v[114:117], v[218:219], off offset:512
	global_load_dwordx4 v[118:121], v[218:219], off
	s_waitcnt lgkmcnt(6)
; #define SBAR() __builtin_amdgcn_sched_barrier(0)
; template <int OFF> __device__ __forceinline__ s16x4 tr_read(int vb) {
;   s16x4 r; asm volatile("ds_read_b64_tr_b16 %0, %1 offset:%2" : "=&v"(r) : "v"(vb), "i"(OFF) : "memory"); return r;
; }
; template <int D0> __device__ __forceinline__ void pv_one(f32x16& od, int vb, bf16x8 pa0, bf16x8 pa1, bf16x8 pa2, bf16x8 pa3) {
;   const s16x4 l0 = tr_read<v_rd_off(D0, 0, 0)>(vb), h0 = tr_read<v_rd_off(D0, 0, 1)>(vb), l1 = tr_read<v_rd_off(D0, 1, 0)>(vb), h1 = tr_read<v_rd_off(D0, 1, 1)>(vb);
;   const s16x4 l2 = tr_read<v_rd_off(D0, 2, 0)>(vb), h2 = tr_read<v_rd_off(D0, 2, 1)>(vb), l3 = tr_read<v_rd_off(D0, 3, 0)>(vb), h3 = tr_read<v_rd_off(D0, 3, 1)>(vb);
;   asm volatile("s_waitcnt lgkmcnt(0)" ::: "memory"); SBAR();
;     ...
;   od = __builtin_amdgcn_mfma_f32_32x32x16_bf16(pa0, PK(l0, h0), od, 0, 0, 0);
;   od = __builtin_amdgcn_mfma_f32_32x32x16_bf16(pa1, PK(l1, h1), od, 0, 0, 0);
;   od = __builtin_amdgcn_mfma_f32_32x32x16_bf16(pa2, PK(l2, h2), od, 0, 0, 0);
;   od = __builtin_amdgcn_mfma_f32_32x32x16_bf16(pa3, PK(l3, h3), od, 0, 0, 0);
;     ...
; }
; __device__ __forceinline__ void pv_d0(f32x16* o, int vb, bf16x8 pa0, bf16x8 pa1, bf16x8 pa2, bf16x8 pa3) {
;   pv_one<0>(o[0], vb, pa0, pa1, pa2, pa3); pv_one<1>(o[1], vb, pa0, pa1, pa2, pa3); pv_one<2>(o[2], vb, pa0, pa1, pa2, pa3); pv_one<3>(o[3], vb, pa0, pa1, pa2, pa3);
; }
	v_mfma_f32_32x32x16_bf16 v[2:17], v[178:181], v[206:209], v[2:17]
	ds_read_b64_tr_b16 v[206:207], v190 offset:0x1000
	ds_read_b64_tr_b16 v[208:209], v190 offset:0x1800
	v_add_co_u32_e32 v218, vcc, s81, v186
	s_nop 1
	v_addc_co_u32_e32 v219, vcc, 0, v187, vcc
	global_load_dwordx4 v[126:129], v[218:219], off offset:512
	global_load_dwordx4 v[122:125], v[218:219], off
	s_waitcnt lgkmcnt(6)
	v_mfma_f32_32x32x16_bf16 v[50:65], v[178:181], v[232:235], v[50:65]
	ds_read_b64_tr_b16 v[232:233], v190 offset:0x1200
	ds_read_b64_tr_b16 v[234:235], v190 offset:0x1a00
	s_waitcnt lgkmcnt(6)
	v_mfma_f32_32x32x16_bf16 v[34:49], v[178:181], v[236:239], v[34:49]
	ds_read_b64_tr_b16 v[236:237], v190 offset:0x1400
	ds_read_b64_tr_b16 v[238:239], v190 offset:0x1c00
	s_waitcnt lgkmcnt(6)
	v_mfma_f32_32x32x16_bf16 v[18:33], v[178:181], v[240:243], v[18:33]
	ds_read_b64_tr_b16 v[240:241], v190 offset:0x1600
	ds_read_b64_tr_b16 v[242:243], v190 offset:0x1e00
	s_waitcnt lgkmcnt(6)
	v_mfma_f32_32x32x16_bf16 v[2:17], v[182:185], v[206:209], v[2:17]
	ds_read_b64_tr_b16 v[206:207], v190 offset:0x2000
	ds_read_b64_tr_b16 v[208:209], v190 offset:0x2800
	v_max_f32_e32 v218, v130, v131
	v_max3_f32 v218, v218, v132, v133
	s_waitcnt lgkmcnt(6)
	v_mfma_f32_32x32x16_bf16 v[50:65], v[182:185], v[232:235], v[50:65]
	ds_read_b64_tr_b16 v[232:233], v190 offset:0x2200
	ds_read_b64_tr_b16 v[234:235], v190 offset:0x2a00
	v_max3_f32 v218, v218, v134, v135
	v_max3_f32 v218, v218, v136, v137
	s_waitcnt lgkmcnt(6)
	v_mfma_f32_32x32x16_bf16 v[34:49], v[182:185], v[236:239], v[34:49]
	ds_read_b64_tr_b16 v[236:237], v190 offset:0x2400
	ds_read_b64_tr_b16 v[238:239], v190 offset:0x2c00
	v_max3_f32 v218, v218, v138, v139
	v_max3_f32 v218, v218, v140, v141
	s_waitcnt lgkmcnt(6)
	v_mfma_f32_32x32x16_bf16 v[18:33], v[182:185], v[240:243], v[18:33]
	ds_read_b64_tr_b16 v[240:241], v190 offset:0x2600
	ds_read_b64_tr_b16 v[242:243], v190 offset:0x2e00
	v_max3_f32 v218, v218, v142, v143
	v_max3_f32 v218, v218, v144, v145
	s_waitcnt lgkmcnt(6)
	v_mfma_f32_32x32x16_bf16 v[2:17], v[198:201], v[206:209], v[2:17]
	ds_read_b64_tr_b16 v[206:207], v190 offset:0x3000
	ds_read_b64_tr_b16 v[208:209], v190 offset:0x3800
	v_max3_f32 v218, v218, v98, v99
	v_max3_f32 v218, v218, v100, v101
	s_waitcnt lgkmcnt(6)
	v_mfma_f32_32x32x16_bf16 v[50:65], v[198:201], v[232:235], v[50:65]
	ds_read_b64_tr_b16 v[232:233], v190 offset:0x3200
	ds_read_b64_tr_b16 v[234:235], v190 offset:0x3a00
	v_max3_f32 v218, v218, v102, v103
	v_max3_f32 v218, v218, v104, v105
	s_waitcnt lgkmcnt(6)
	v_mfma_f32_32x32x16_bf16 v[34:49], v[198:201], v[236:239], v[34:49]
	ds_read_b64_tr_b16 v[236:237], v190 offset:0x3400
	ds_read_b64_tr_b16 v[238:239], v190 offset:0x3c00
	v_max3_f32 v218, v218, v106, v107
	s_waitcnt lgkmcnt(6)
	v_mfma_f32_32x32x16_bf16 v[18:33], v[198:201], v[240:243], v[18:33]
	ds_read_b64_tr_b16 v[240:241], v190 offset:0x3600
	ds_read_b64_tr_b16 v[242:243], v190 offset:0x3e00
	v_max3_f32 v218, v218, v108, v109
	s_waitcnt lgkmcnt(6)
	v_mfma_f32_32x32x16_bf16 v[2:17], v[202:205], v[206:209], v[2:17]
	v_max3_f32 v218, v218, v110, v111
	s_waitcnt lgkmcnt(4)
	v_mfma_f32_32x32x16_bf16 v[50:65], v[202:205], v[232:235], v[50:65]
	v_max3_f32 v218, v218, v112, v113
	s_waitcnt lgkmcnt(2)
	v_mfma_f32_32x32x16_bf16 v[34:49], v[202:205], v[236:239], v[34:49]
	v_mov_b32_e32 v219, v218
	s_waitcnt lgkmcnt(0)
	v_mfma_f32_32x32x16_bf16 v[18:33], v[202:205], v[240:243], v[18:33]
	v_permlane32_swap_b32_e32 v218, v219
	v_max_f32_e32 v179, v218, v219
.Ljoin_g2:
	v_cmp_ge_f32_e32 vcc, s30, v179
	s_cmp_eq_u64 vcc, exec
	v_mov_b32_e32 v178, 1.0
	s_cbranch_scc0 .LBB0_91
.LBB0_78:
	s_barrier
	s_waitcnt vmcnt(0)
	v_cmp_gt_f32_e32 vcc, 1.0, v178
	s_waitcnt vmcnt(3)
	ds_write_b128 v191, v[114:117] offset:16384
	s_waitcnt vmcnt(1)
	ds_write_b128 v192, v[126:129] offset:16384
	ds_write_b128 v212, v[118:121] offset:49152
	s_waitcnt vmcnt(0)
	ds_write_b128 v213, v[122:125] offset:49152
	s_cbranch_vccnz .Lresc_g2

.Lresc_g1:
	s_and_saveexec_b64 s[0:1], s[40:41]
	ds_write_b32 v188, v229 offset:128
	s_or_b64 exec, exec, s[0:1]
	s_waitcnt lgkmcnt(0)
	v_add_u32_e32 v110, s11, v0
	ds_read_b128 v[98:101], v110 offset:128
	ds_read_b128 v[102:105], v110 offset:160
	ds_read_b128 v[106:109], v110 offset:192
	ds_read_b128 v[110:113], v110 offset:224
	s_waitcnt lgkmcnt(3)
	v_pk_mul_f32 v[50:51], v[98:99], v[50:51]
	v_pk_mul_f32 v[52:53], v[52:53], v[100:101]
	s_waitcnt lgkmcnt(2)
	v_pk_mul_f32 v[54:55], v[54:55], v[102:103]
	v_pk_mul_f32 v[56:57], v[56:57], v[104:105]
	s_waitcnt lgkmcnt(1)
	v_pk_mul_f32 v[58:59], v[58:59], v[106:107]
	v_pk_mul_f32 v[60:61], v[60:61], v[108:109]
	s_waitcnt lgkmcnt(0)
	v_pk_mul_f32 v[62:63], v[62:63], v[110:111]
	v_pk_mul_f32 v[14:15], v[14:15], v[110:111]
	v_pk_mul_f32 v[10:11], v[10:11], v[106:107]
	v_pk_mul_f32 v[6:7], v[6:7], v[102:103]
	v_pk_mul_f32 v[16:17], v[16:17], v[112:113]
	v_pk_mul_f32 v[12:13], v[12:13], v[108:109]
	v_pk_mul_f32 v[8:9], v[8:9], v[104:105]
	v_pk_mul_f32 v[4:5], v[4:5], v[100:101]
	v_pk_mul_f32 v[2:3], v[2:3], v[98:99]
	v_pk_mul_f32 v[64:65], v[64:65], v[112:113]
	v_pk_mul_f32 v[18:19], v[98:99], v[18:19]
	v_pk_mul_f32 v[20:21], v[20:21], v[100:101]
	v_pk_mul_f32 v[22:23], v[22:23], v[102:103]
	v_pk_mul_f32 v[24:25], v[24:25], v[104:105]
	v_pk_mul_f32 v[26:27], v[26:27], v[106:107]
	v_pk_mul_f32 v[28:29], v[28:29], v[108:109]
	v_pk_mul_f32 v[30:31], v[30:31], v[110:111]
	v_pk_mul_f32 v[46:47], v[46:47], v[110:111]
	v_pk_mul_f32 v[42:43], v[42:43], v[106:107]
	v_pk_mul_f32 v[38:39], v[38:39], v[102:103]
	v_pk_mul_f32 v[48:49], v[48:49], v[112:113]
	v_pk_mul_f32 v[44:45], v[44:45], v[108:109]
	v_pk_mul_f32 v[40:41], v[40:41], v[104:105]
	v_pk_mul_f32 v[36:37], v[36:37], v[100:101]
	v_pk_mul_f32 v[34:35], v[34:35], v[98:99]
	v_pk_mul_f32 v[32:33], v[32:33], v[112:113]
	s_branch .LBB0_76
.Lresc_g2:
	s_and_saveexec_b64 s[0:1], s[40:41]
	ds_write_b32 v188, v178 offset:128
	s_or_b64 exec, exec, s[0:1]
	s_waitcnt lgkmcnt(0)
	v_add_u32_e32 v126, s11, v0
	ds_read_b128 v[114:117], v126 offset:128
	ds_read_b128 v[118:121], v126 offset:160
	ds_read_b128 v[122:125], v126 offset:192
	ds_read_b128 v[126:129], v126 offset:224
	s_waitcnt lgkmcnt(3)
	v_pk_mul_f32 v[50:51], v[114:115], v[50:51]
	v_pk_mul_f32 v[52:53], v[52:53], v[116:117]
	s_waitcnt lgkmcnt(2)
	v_pk_mul_f32 v[54:55], v[54:55], v[118:119]
	v_pk_mul_f32 v[56:57], v[56:57], v[120:121]
	s_waitcnt lgkmcnt(1)
	v_pk_mul_f32 v[58:59], v[58:59], v[122:123]
	v_pk_mul_f32 v[60:61], v[60:61], v[124:125]
	s_waitcnt lgkmcnt(0)
	v_pk_mul_f32 v[62:63], v[62:63], v[126:127]
	v_pk_mul_f32 v[14:15], v[14:15], v[126:127]
	v_pk_mul_f32 v[10:11], v[10:11], v[122:123]
	v_pk_mul_f32 v[6:7], v[6:7], v[118:119]
	v_pk_mul_f32 v[16:17], v[16:17], v[128:129]
	v_pk_mul_f32 v[12:13], v[12:13], v[124:125]
	v_pk_mul_f32 v[8:9], v[8:9], v[120:121]
	v_pk_mul_f32 v[4:5], v[4:5], v[116:117]
	v_pk_mul_f32 v[2:3], v[2:3], v[114:115]
	v_pk_mul_f32 v[64:65], v[64:65], v[128:129]
	v_pk_mul_f32 v[18:19], v[114:115], v[18:19]
	v_pk_mul_f32 v[20:21], v[20:21], v[116:117]
	v_pk_mul_f32 v[22:23], v[22:23], v[118:119]
	v_pk_mul_f32 v[24:25], v[24:25], v[120:121]
	v_pk_mul_f32 v[26:27], v[26:27], v[122:123]
	v_pk_mul_f32 v[28:29], v[28:29], v[124:125]
	v_pk_mul_f32 v[30:31], v[30:31], v[126:127]
	v_pk_mul_f32 v[46:47], v[46:47], v[126:127]
	v_pk_mul_f32 v[42:43], v[42:43], v[122:123]
	v_pk_mul_f32 v[38:39], v[38:39], v[118:119]
	v_pk_mul_f32 v[48:49], v[48:49], v[128:129]
	v_pk_mul_f32 v[44:45], v[44:45], v[124:125]
	v_pk_mul_f32 v[40:41], v[40:41], v[120:121]
	v_pk_mul_f32 v[36:37], v[36:37], v[116:117]
	v_pk_mul_f32 v[34:35], v[34:35], v[114:115]
	v_pk_mul_f32 v[32:33], v[32:33], v[128:129]
	s_branch .LBB0_82

; template <bool FIRST> __device__ __forceinline__ void partialSM(f32x16& p0, f32x16& p1, float& m_reg, float& alpha, f32x16& negm, float c_cur) {
;   float pmax = p0[0];
; #pragma unroll
;   for (int r = 1; r < 16; ++r) pmax = fmaxf(pmax, p0[r]);
; #pragma unroll
;   for (int r = 0; r < 16; ++r) pmax = fmaxf(pmax, p1[r]);
;   { auto rr = __builtin_amdgcn_permlane32_swap(__float_as_uint(pmax), __float_as_uint(pmax), false, false);
;     pmax = fmaxf(__uint_as_float(rr[0]), __uint_as_float(rr[1])); }
.LBB0_70:
	v_max_f32_e32 v66, v131, v131
	v_max_f32_e32 v67, v130, v130
	v_max_f32_e32 v66, v67, v66
	v_max3_f32 v66, v66, v132, v133
	v_max3_f32 v66, v66, v134, v135
	v_max3_f32 v66, v66, v136, v137
	v_max3_f32 v66, v66, v138, v139
	v_max3_f32 v66, v66, v140, v141
	v_max3_f32 v66, v66, v142, v143
	v_max3_f32 v66, v66, v144, v145
	v_max3_f32 v66, v66, v114, v115
	v_max3_f32 v66, v66, v116, v117
	v_max3_f32 v66, v66, v118, v119
	v_max3_f32 v66, v66, v120, v121
	v_max3_f32 v66, v66, v122, v123
	v_max3_f32 v66, v66, v124, v125
	v_max3_f32 v66, v66, v126, v127
	v_max3_f32 v66, v66, v128, v129
	v_mov_b32_e32 v67, v66
	s_nop 1
	v_permlane32_swap_b32_e32 v66, v67
	v_max_f32_e32 v67, v67, v67
	v_max_f32_e32 v66, v66, v66
	v_max_f32_e32 v66, v66, v67
	s_branch .Ljoin_g1

; template <bool FIRST> __device__ __forceinline__ void partialSM(f32x16& p0, f32x16& p1, float& m_reg, float& alpha, f32x16& negm, float c_cur) {
;   float pmax = p0[0];
; #pragma unroll
;   for (int r = 1; r < 16; ++r) pmax = fmaxf(pmax, p0[r]);
; #pragma unroll
;   for (int r = 0; r < 16; ++r) pmax = fmaxf(pmax, p1[r]);
;   { auto rr = __builtin_amdgcn_permlane32_swap(__float_as_uint(pmax), __float_as_uint(pmax), false, false);
;     pmax = fmaxf(__uint_as_float(rr[0]), __uint_as_float(rr[1])); }
.LBB0_77:
	v_max_f32_e32 v178, v131, v131
	v_max_f32_e32 v179, v130, v130
	v_max_f32_e32 v178, v179, v178
	v_max3_f32 v178, v178, v132, v133
	v_max3_f32 v178, v178, v134, v135
	v_max3_f32 v178, v178, v136, v137
	v_max3_f32 v178, v178, v138, v139
	v_max3_f32 v178, v178, v140, v141
	v_max3_f32 v178, v178, v142, v143
	v_max3_f32 v178, v178, v144, v145
	v_max3_f32 v178, v178, v98, v99
	v_max3_f32 v178, v178, v100, v101
	v_max3_f32 v178, v178, v102, v103
	v_max3_f32 v178, v178, v104, v105
	v_max3_f32 v178, v178, v106, v107
	v_max3_f32 v178, v178, v108, v109
	v_max3_f32 v178, v178, v110, v111
	v_max3_f32 v178, v178, v112, v113
	v_mov_b32_e32 v179, v178
	s_nop 1
	v_permlane32_swap_b32_e32 v178, v179
	v_max_f32_e32 v179, v179, v179
	v_max_f32_e32 v178, v178, v178
	v_max_f32_e32 v179, v178, v179
	s_branch .Ljoin_g2

; __device__ __forceinline__ void finishSM(f32x16& p0, f32x16& p1, float alpha, float& l_reg, bf16x8& pa0, bf16x8& pa1, bf16x8& pa2, bf16x8& pa3) {
; #pragma unroll
;   for (int r = 0; r < 16; ++r) p1[r] = __builtin_amdgcn_exp2f(p1[r]);
;   float ps = 0;
; #pragma unroll
;   for (int r = 0; r < 16; ++r) ps += p0[r];
; #pragma unroll
;   for (int r = 0; r < 16; ++r) ps += p1[r];
;   { auto rr = __builtin_amdgcn_permlane32_swap(__float_as_uint(ps), __float_as_uint(ps), false, false);
;     ps = __uint_as_float(rr[0]) + __uint_as_float(rr[1]); }
;   l_reg = l_reg * alpha + ps;
;     ...
;   PK4(p0, 0, pa0); PK4(p0, 8, pa1); PK4(p1, 0, pa2); PK4(p1, 8, pa3);
;     ...
; }
; template <int DQK> __device__ __forceinline__ void qkt(f32x16& p0, f32x16& p1, const char* Ks, const bf16x8* qr, int r32, int hi, const f32x16& negm) {
; #pragma unroll
;   for (int d0 = 0; d0 < DQK / 16; ++d0) { const int cb = (d0 * 16 + hi * 8) * 2;
;     const bf16x8 b0 = *reinterpret_cast<const bf16x8*>(Ks + (DQK == 128 ? KSWZ(r32, cb) : KSWZ64(r32, cb)));
;     const bf16x8 b1 = *reinterpret_cast<const bf16x8*>(Ks + (DQK == 128 ? KSWZ(32 + r32, cb) : KSWZ64(32 + r32, cb)));
;     if (d0 == 0) { p0 = __builtin_amdgcn_mfma_f32_32x32x16_bf16(b0, qr[0], negm, 0, 0, 0); p1 = __builtin_amdgcn_mfma_f32_32x32x16_bf16(b1, qr[0], negm, 0, 0, 0); }
;     else { p0 = __builtin_amdgcn_mfma_f32_32x32x16_bf16(b0, qr[d0], p0, 0, 0, 0); p1 = __builtin_amdgcn_mfma_f32_32x32x16_bf16(b1, qr[d0], p1, 0, 0, 0); } }
; }
; __device__ __forceinline__ int v_st(int k, int c) { const int kk = (k & ~0xC) | ((k & 4) << 1) | ((k & 8) >> 1); return ((kk >> 3) * 4 + (c >> 5)) * 512 + ((kk & 7) * 32 + (c & 31)) * 2; }
; __device__ __forceinline__ int v_rd_base(int lane) { return ((lane & 3) << 3) | (((lane >> 2) & 3) << 6) | (((lane >> 4) & 1) << 5) | (((lane >> 5) & 1) << 8); }
; template <int OFF> __device__ __forceinline__ s16x4 tr_read(int vb) {
;   s16x4 r; asm volatile("ds_read_b64_tr_b16 %0, %1 offset:%2" : "=&v"(r) : "v"(vb), "i"(OFF) : "memory"); return r;
; }
; template <int D0> __device__ __forceinline__ void pv_one(f32x16& od, int vb, bf16x8 pa0, bf16x8 pa1, bf16x8 pa2, bf16x8 pa3) {
;   const s16x4 l0 = tr_read<v_rd_off(D0, 0, 0)>(vb), h0 = tr_read<v_rd_off(D0, 0, 1)>(vb), l1 = tr_read<v_rd_off(D0, 1, 0)>(vb), h1 = tr_read<v_rd_off(D0, 1, 1)>(vb);
.Lcret_f1:
	s_waitcnt lgkmcnt(4)
	v_mfma_f32_32x32x16_bf16 v[84:99], v[116:119], v[162:165], v[236:251]
	v_mfma_f32_32x32x16_bf16 v[116:131], v[180:183], v[162:165], v[236:251]
	ds_read_b128 v[180:183], v226 offset:53248
	v_add_f32_e32 v0, 0, v148
	v_add_f32_e32 v0, v178, v0
	v_add_f32_e32 v0, v146, v0
	v_add_f32_e32 v0, v149, v0
	v_add_f32_e32 v0, v144, v0
	v_add_f32_e32 v0, v147, v0
	v_add_f32_e32 v0, v143, v0
	v_add_f32_e32 v0, v145, v0
	v_add_f32_e32 v0, v137, v0
	v_add_f32_e32 v0, v139, v0
	s_waitcnt lgkmcnt(3)
	v_mfma_f32_32x32x16_bf16 v[116:131], v[184:187], v[158:161], v[116:131]
	v_add_f32_e32 v0, v136, v0
	v_add_f32_e32 v0, v138, v0
	v_add_f32_e32 v0, v135, v0
	v_add_f32_e32 v0, v142, v0
	v_add_f32_e32 v0, v140, v0
	v_add_f32_e32 v0, v141, v0
	v_mfma_f32_32x32x16_bf16 v[84:99], v[68:71], v[158:161], v[84:99]
	ds_read_b128 v[184:187], v226 offset:49152
	v_cvt_pk_bf16_f32 v76, v148, v178
	v_cvt_pk_bf16_f32 v77, v146, v149
	v_cvt_pk_bf16_f32 v78, v144, v147
	v_cvt_pk_bf16_f32 v79, v143, v145
	v_lshl_add_u64 v[148:149], v[194:195], 0, s[0:1]
	v_lshl_add_u64 v[196:197], v[192:193], 0, s[0:1]
	s_waitcnt lgkmcnt(2)
	v_mfma_f32_32x32x16_bf16 v[116:131], v[72:75], v[154:157], v[116:131]
	v_cvt_pk_bf16_f32 v80, v137, v139
	v_cvt_pk_bf16_f32 v81, v136, v138
	v_cvt_pk_bf16_f32 v82, v135, v142
	v_cvt_pk_bf16_f32 v83, v140, v141
	s_mov_b32 s4, 0x102b1000
	v_add_co_u32_e64 v132, s[4:5], s4, v148
	v_mfma_f32_32x32x16_bf16 v[84:99], v[206:209], v[154:157], v[84:99]
	ds_read_b64_tr_b16 v[134:135], v223 offset:0
	ds_read_b64_tr_b16 v[136:137], v223 offset:0x800
	ds_read_b64_tr_b16 v[138:139], v223 offset:0x200
	ds_read_b64_tr_b16 v[140:141], v223 offset:0xa00
	ds_read_b64_tr_b16 v[142:143], v223 offset:0x400
	ds_read_b64_tr_b16 v[144:145], v223 offset:0xc00
	ds_read_b64_tr_b16 v[198:199], v223 offset:0x600
	ds_read_b64_tr_b16 v[200:201], v223 offset:0xe00
	v_permlane32_swap_b32_e32 v76, v78
	v_permlane32_swap_b32_e32 v77, v79
	v_addc_co_u32_e64 v133, s[4:5], 0, v149, s[4:5]
	s_mov_b32 s4, 0x102f9000
	v_add_co_u32_e64 v202, s[4:5], s4, v148
	s_waitcnt lgkmcnt(8)
	v_mfma_f32_32x32x16_bf16 v[116:131], v[180:183], v[150:153], v[116:131]
	v_addc_co_u32_e64 v203, s[4:5], 0, v149, s[4:5]
	s_mov_b32 s4, 0x102b0000
	v_add_co_u32_e64 v204, s[4:5], s4, v196
	v_permlane32_swap_b32_e32 v80, v82
	v_permlane32_swap_b32_e32 v81, v83
	v_mfma_f32_32x32x16_bf16 v[84:99], v[184:187], v[150:153], v[84:99]
	v_addc_co_u32_e64 v205, s[4:5], 0, v197, s[4:5]
	global_load_dwordx4 v[178:181], v[132:133], off
	global_load_dwordx4 v[182:185], v[202:203], off
	global_load_dwordx4 v[186:189], v[204:205], off offset:2048
	s_waitcnt lgkmcnt(6)
	v_mfma_f32_32x32x16_bf16 v[50:65], v[76:79], v[134:137], v[50:65]
	ds_read_b64_tr_b16 v[134:135], v223 offset:0x1000
	ds_read_b64_tr_b16 v[136:137], v223 offset:0x1800
	v_exp_f32_e32 v68, v100
	v_exp_f32_e32 v69, v101
	v_add_f32_e32 v0, v68, v0
	s_waitcnt lgkmcnt(6)
	v_mfma_f32_32x32x16_bf16 v[34:49], v[76:79], v[138:141], v[34:49]
	ds_read_b64_tr_b16 v[138:139], v223 offset:0x1200
	ds_read_b64_tr_b16 v[140:141], v223 offset:0x1a00
	v_exp_f32_e32 v70, v102
	v_add_f32_e32 v0, v69, v0
	v_exp_f32_e32 v71, v103
	v_add_f32_e32 v0, v70, v0
	s_waitcnt lgkmcnt(6)
	v_mfma_f32_32x32x16_bf16 v[18:33], v[76:79], v[142:145], v[18:33]
	ds_read_b64_tr_b16 v[142:143], v223 offset:0x1400
	ds_read_b64_tr_b16 v[144:145], v223 offset:0x1c00
	v_exp_f32_e32 v72, v104
	v_add_f32_e32 v0, v71, v0
	v_exp_f32_e32 v73, v105
	v_add_f32_e32 v0, v72, v0
	s_waitcnt lgkmcnt(6)
	v_mfma_f32_32x32x16_bf16 v[2:17], v[76:79], v[198:201], v[2:17]
	ds_read_b64_tr_b16 v[198:199], v223 offset:0x1600
	ds_read_b64_tr_b16 v[200:201], v223 offset:0x1e00
	v_exp_f32_e32 v74, v106
	v_add_f32_e32 v0, v73, v0
	v_exp_f32_e32 v75, v107
	v_add_f32_e32 v0, v74, v0
	v_add_f32_e32 v0, v75, v0
	s_waitcnt lgkmcnt(6)
; #define SBAR() __builtin_amdgcn_sched_barrier(0)
; template <int OFF> __device__ __forceinline__ s16x4 tr_read(int vb) {
;   s16x4 r; asm volatile("ds_read_b64_tr_b16 %0, %1 offset:%2" : "=&v"(r) : "v"(vb), "i"(OFF) : "memory"); return r;
; }
; template <int D0> __device__ __forceinline__ void pv_one(f32x16& od, int vb, bf16x8 pa0, bf16x8 pa1, bf16x8 pa2, bf16x8 pa3) {
;   const s16x4 l0 = tr_read<v_rd_off(D0, 0, 0)>(vb), h0 = tr_read<v_rd_off(D0, 0, 1)>(vb), l1 = tr_read<v_rd_off(D0, 1, 0)>(vb), h1 = tr_read<v_rd_off(D0, 1, 1)>(vb);
;   const s16x4 l2 = tr_read<v_rd_off(D0, 2, 0)>(vb), h2 = tr_read<v_rd_off(D0, 2, 1)>(vb), l3 = tr_read<v_rd_off(D0, 3, 0)>(vb), h3 = tr_read<v_rd_off(D0, 3, 1)>(vb);
;   asm volatile("s_waitcnt lgkmcnt(0)" ::: "memory"); SBAR();
;     ...
;   od = __builtin_amdgcn_mfma_f32_32x32x16_bf16(pa0, PK(l0, h0), od, 0, 0, 0);
;   od = __builtin_amdgcn_mfma_f32_32x32x16_bf16(pa1, PK(l1, h1), od, 0, 0, 0);
;   od = __builtin_amdgcn_mfma_f32_32x32x16_bf16(pa2, PK(l2, h2), od, 0, 0, 0);
;   od = __builtin_amdgcn_mfma_f32_32x32x16_bf16(pa3, PK(l3, h3), od, 0, 0, 0);
;     ...
; }
; __device__ __forceinline__ void pv_d0(f32x16* o, int vb, bf16x8 pa0, bf16x8 pa1, bf16x8 pa2, bf16x8 pa3) {
;   pv_one<0>(o[0], vb, pa0, pa1, pa2, pa3); pv_one<1>(o[1], vb, pa0, pa1, pa2, pa3); pv_one<2>(o[2], vb, pa0, pa1, pa2, pa3); pv_one<3>(o[3], vb, pa0, pa1, pa2, pa3);
; }
	v_mfma_f32_32x32x16_bf16 v[50:65], v[80:83], v[134:137], v[50:65]
	ds_read_b64_tr_b16 v[134:135], v223 offset:0x2000
	ds_read_b64_tr_b16 v[136:137], v223 offset:0x2800
	v_cvt_pk_bf16_f32 v100, v68, v69
	v_cvt_pk_bf16_f32 v101, v70, v71
	v_cvt_pk_bf16_f32 v102, v72, v73
	v_cvt_pk_bf16_f32 v103, v74, v75
	s_waitcnt lgkmcnt(6)
	v_mfma_f32_32x32x16_bf16 v[34:49], v[80:83], v[138:141], v[34:49]
	ds_read_b64_tr_b16 v[138:139], v223 offset:0x2200
	ds_read_b64_tr_b16 v[140:141], v223 offset:0x2a00
	v_exp_f32_e32 v68, v108
	v_exp_f32_e32 v69, v109
	v_permlane32_swap_b32_e32 v100, v102
	v_permlane32_swap_b32_e32 v101, v103
	s_waitcnt lgkmcnt(6)
	v_mfma_f32_32x32x16_bf16 v[18:33], v[80:83], v[142:145], v[18:33]
	ds_read_b64_tr_b16 v[142:143], v223 offset:0x2400
	ds_read_b64_tr_b16 v[144:145], v223 offset:0x2c00
	v_exp_f32_e32 v70, v110
	v_exp_f32_e32 v71, v111
	v_exp_f32_e32 v72, v112
	s_waitcnt lgkmcnt(6)
	v_mfma_f32_32x32x16_bf16 v[2:17], v[80:83], v[198:201], v[2:17]
	ds_read_b64_tr_b16 v[198:199], v223 offset:0x2600
	ds_read_b64_tr_b16 v[200:201], v223 offset:0x2e00
	v_exp_f32_e32 v73, v113
	v_exp_f32_e32 v74, v114
	v_exp_f32_e32 v75, v115
	s_waitcnt lgkmcnt(6)
	v_mfma_f32_32x32x16_bf16 v[50:65], v[100:103], v[134:137], v[50:65]
	ds_read_b64_tr_b16 v[134:135], v223 offset:0x3000
	ds_read_b64_tr_b16 v[136:137], v223 offset:0x3800
	v_add_f32_e32 v0, v68, v0
	v_add_f32_e32 v0, v69, v0
	v_add_f32_e32 v0, v70, v0
	v_add_f32_e32 v0, v71, v0
	s_waitcnt lgkmcnt(6)
	v_mfma_f32_32x32x16_bf16 v[34:49], v[100:103], v[138:141], v[34:49]
	ds_read_b64_tr_b16 v[138:139], v223 offset:0x3200
	ds_read_b64_tr_b16 v[140:141], v223 offset:0x3a00
	v_add_f32_e32 v0, v72, v0
	v_add_f32_e32 v0, v73, v0
	v_add_f32_e32 v0, v74, v0
	v_add_f32_e32 v0, v75, v0
	v_mov_b32_e32 v231, v0
	s_waitcnt lgkmcnt(6)
	v_mfma_f32_32x32x16_bf16 v[18:33], v[100:103], v[142:145], v[18:33]
	ds_read_b64_tr_b16 v[142:143], v223 offset:0x3400
	ds_read_b64_tr_b16 v[144:145], v223 offset:0x3c00
	v_cvt_pk_bf16_f32 v104, v68, v69
	v_cvt_pk_bf16_f32 v105, v70, v71
	v_cvt_pk_bf16_f32 v106, v72, v73
	v_cvt_pk_bf16_f32 v107, v74, v75
	v_permlane32_swap_b32_e32 v0, v231
	v_max_f32_e32 v132, v84, v85
	v_max3_f32 v132, v132, v86, v87
	s_waitcnt lgkmcnt(6)
	v_mfma_f32_32x32x16_bf16 v[2:17], v[100:103], v[198:201], v[2:17]
	ds_read_b64_tr_b16 v[198:199], v223 offset:0x3600
	ds_read_b64_tr_b16 v[200:201], v223 offset:0x3e00
	v_permlane32_swap_b32_e32 v104, v106
	v_permlane32_swap_b32_e32 v105, v107
	v_max3_f32 v132, v132, v88, v89
	v_max3_f32 v132, v132, v90, v91
	v_max3_f32 v132, v132, v92, v93
	s_waitcnt lgkmcnt(6)
	v_mfma_f32_32x32x16_bf16 v[50:65], v[104:107], v[134:137], v[50:65]
	v_max3_f32 v132, v132, v94, v95
	v_max3_f32 v132, v132, v96, v97
	v_max3_f32 v132, v132, v98, v99
	v_max3_f32 v132, v132, v116, v117
	v_max3_f32 v132, v132, v118, v119
	s_waitcnt lgkmcnt(4)
	v_mfma_f32_32x32x16_bf16 v[34:49], v[104:107], v[138:141], v[34:49]
	v_max3_f32 v132, v132, v120, v121
	v_max3_f32 v132, v132, v122, v123
	v_max3_f32 v132, v132, v124, v125
	v_max3_f32 v132, v132, v126, v127
	v_max3_f32 v132, v132, v128, v129
	v_max3_f32 v132, v132, v130, v131
	v_mov_b32_e32 v133, v132
	s_waitcnt lgkmcnt(2)
	v_mfma_f32_32x32x16_bf16 v[18:33], v[104:107], v[142:145], v[18:33]
	v_permlane32_swap_b32_e32 v132, v133
	v_max_f32_e32 v100, v132, v133
	v_cmp_ge_f32_e32 vcc, s30, v100
	s_waitcnt lgkmcnt(0)
	v_mfma_f32_32x32x16_bf16 v[2:17], v[104:107], v[198:201], v[2:17]
	s_cmp_lg_u64 vcc, exec
	s_cbranch_scc1 .LBB0_255
.LBB0_223:
	v_mov_b32_e32 v232, 1.0
	v_mov_b32_e32 v234, v233
.LBB0_225:
	s_barrier
	s_waitcnt vmcnt(3)
	v_cmp_gt_f32_e32 vcc, 1.0, v232
	s_waitcnt vmcnt(3)
	ds_write_b128 v212, v[166:169]
	ds_write_b128 v213, v[170:173]
	ds_write_b128 v229, v[174:177] offset:32768
	s_cbranch_vccnz .Lresc_h1

; #define SBAR() __builtin_amdgcn_sched_barrier(0)
; template <int OFF> __device__ __forceinline__ s16x4 tr_read(int vb) {
;   s16x4 r; asm volatile("ds_read_b64_tr_b16 %0, %1 offset:%2" : "=&v"(r) : "v"(vb), "i"(OFF) : "memory"); return r;
; }
; template <int D0> __device__ __forceinline__ void pv_one(f32x16& od, int vb, bf16x8 pa0, bf16x8 pa1, bf16x8 pa2, bf16x8 pa3) {
;   const s16x4 l0 = tr_read<v_rd_off(D0, 0, 0)>(vb), h0 = tr_read<v_rd_off(D0, 0, 1)>(vb), l1 = tr_read<v_rd_off(D0, 1, 0)>(vb), h1 = tr_read<v_rd_off(D0, 1, 1)>(vb);
;   const s16x4 l2 = tr_read<v_rd_off(D0, 2, 0)>(vb), h2 = tr_read<v_rd_off(D0, 2, 1)>(vb), l3 = tr_read<v_rd_off(D0, 3, 0)>(vb), h3 = tr_read<v_rd_off(D0, 3, 1)>(vb);
;   asm volatile("s_waitcnt lgkmcnt(0)" ::: "memory"); SBAR();
;     ...
;   od = __builtin_amdgcn_mfma_f32_32x32x16_bf16(pa0, PK(l0, h0), od, 0, 0, 0);
;   od = __builtin_amdgcn_mfma_f32_32x32x16_bf16(pa1, PK(l1, h1), od, 0, 0, 0);
;   od = __builtin_amdgcn_mfma_f32_32x32x16_bf16(pa2, PK(l2, h2), od, 0, 0, 0);
;   od = __builtin_amdgcn_mfma_f32_32x32x16_bf16(pa3, PK(l3, h3), od, 0, 0, 0);
;     ...
; }
; __device__ __forceinline__ void pv_d0(f32x16* o, int vb, bf16x8 pa0, bf16x8 pa1, bf16x8 pa2, bf16x8 pa3) {
;   pv_one<0>(o[0], vb, pa0, pa1, pa2, pa3); pv_one<1>(o[1], vb, pa0, pa1, pa2, pa3); pv_one<2>(o[2], vb, pa0, pa1, pa2, pa3); pv_one<3>(o[3], vb, pa0, pa1, pa2, pa3);
; }
.Lnold_h2:
	s_addk_i32 s19, 0xffa1
	s_waitcnt lgkmcnt(6)
	v_mfma_f32_32x32x16_bf16 v[50:65], v[92:95], v[134:137], v[50:65]
	ds_read_b64_tr_b16 v[134:135], v211 offset:0x1000
	ds_read_b64_tr_b16 v[136:137], v211 offset:0x1800
	v_exp_f32_e32 v84, v116
	v_exp_f32_e32 v85, v117
	v_add_f32_e32 v235, v84, v235
	s_waitcnt lgkmcnt(6)
	v_mfma_f32_32x32x16_bf16 v[34:49], v[92:95], v[138:141], v[34:49]
	ds_read_b64_tr_b16 v[138:139], v211 offset:0x1200
	ds_read_b64_tr_b16 v[140:141], v211 offset:0x1a00
	v_exp_f32_e32 v86, v118
	v_add_f32_e32 v235, v85, v235
	v_exp_f32_e32 v87, v119
	v_add_f32_e32 v235, v86, v235
	s_waitcnt lgkmcnt(6)
	v_mfma_f32_32x32x16_bf16 v[18:33], v[92:95], v[142:145], v[18:33]
	ds_read_b64_tr_b16 v[142:143], v211 offset:0x1400
	ds_read_b64_tr_b16 v[144:145], v211 offset:0x1c00
	v_exp_f32_e32 v88, v120
	v_add_f32_e32 v235, v87, v235
	v_exp_f32_e32 v89, v121
	v_add_f32_e32 v235, v88, v235
	s_waitcnt lgkmcnt(6)
	v_mfma_f32_32x32x16_bf16 v[2:17], v[92:95], v[146:149], v[2:17]
	ds_read_b64_tr_b16 v[146:147], v211 offset:0x1600
	ds_read_b64_tr_b16 v[148:149], v211 offset:0x1e00
	v_exp_f32_e32 v90, v122
	v_add_f32_e32 v235, v89, v235
	v_exp_f32_e32 v91, v123
	v_add_f32_e32 v235, v90, v235
	v_add_f32_e32 v235, v91, v235
	s_waitcnt lgkmcnt(6)
	v_mfma_f32_32x32x16_bf16 v[50:65], v[96:99], v[134:137], v[50:65]
	ds_read_b64_tr_b16 v[134:135], v211 offset:0x2000
	ds_read_b64_tr_b16 v[136:137], v211 offset:0x2800
	v_cvt_pk_bf16_f32 v116, v84, v85
	v_cvt_pk_bf16_f32 v117, v86, v87
	v_cvt_pk_bf16_f32 v118, v88, v89
	v_cvt_pk_bf16_f32 v119, v90, v91
	s_waitcnt lgkmcnt(6)
	v_mfma_f32_32x32x16_bf16 v[34:49], v[96:99], v[138:141], v[34:49]
	ds_read_b64_tr_b16 v[138:139], v211 offset:0x2200
	ds_read_b64_tr_b16 v[140:141], v211 offset:0x2a00
	v_exp_f32_e32 v84, v124
	v_exp_f32_e32 v85, v125
	v_permlane32_swap_b32_e32 v116, v118
	v_permlane32_swap_b32_e32 v117, v119
	s_waitcnt lgkmcnt(6)
	v_mfma_f32_32x32x16_bf16 v[18:33], v[96:99], v[142:145], v[18:33]
	ds_read_b64_tr_b16 v[142:143], v211 offset:0x2400
	ds_read_b64_tr_b16 v[144:145], v211 offset:0x2c00
	v_exp_f32_e32 v86, v126
	v_exp_f32_e32 v87, v127
	v_exp_f32_e32 v88, v128
	s_waitcnt lgkmcnt(6)
	v_mfma_f32_32x32x16_bf16 v[2:17], v[96:99], v[146:149], v[2:17]
	ds_read_b64_tr_b16 v[146:147], v211 offset:0x2600
	ds_read_b64_tr_b16 v[148:149], v211 offset:0x2e00
	v_exp_f32_e32 v89, v129
	v_exp_f32_e32 v90, v130
	v_exp_f32_e32 v91, v131
	s_waitcnt lgkmcnt(6)
	v_mfma_f32_32x32x16_bf16 v[50:65], v[116:119], v[134:137], v[50:65]
	ds_read_b64_tr_b16 v[134:135], v211 offset:0x3000
	ds_read_b64_tr_b16 v[136:137], v211 offset:0x3800
	v_add_f32_e32 v235, v84, v235
	v_add_f32_e32 v235, v85, v235
	v_add_f32_e32 v235, v86, v235
	v_add_f32_e32 v235, v87, v235
	s_waitcnt lgkmcnt(6)
	v_mfma_f32_32x32x16_bf16 v[34:49], v[116:119], v[138:141], v[34:49]
	ds_read_b64_tr_b16 v[138:139], v211 offset:0x3200
	ds_read_b64_tr_b16 v[140:141], v211 offset:0x3a00
	v_add_f32_e32 v235, v88, v235
	v_add_f32_e32 v235, v89, v235
	v_add_f32_e32 v235, v90, v235
	v_add_f32_e32 v235, v91, v235
	v_mov_b32_e32 v252, v235
	s_waitcnt lgkmcnt(6)
	v_mfma_f32_32x32x16_bf16 v[18:33], v[116:119], v[142:145], v[18:33]
	ds_read_b64_tr_b16 v[142:143], v211 offset:0x3400
	ds_read_b64_tr_b16 v[144:145], v211 offset:0x3c00
	v_cvt_pk_bf16_f32 v120, v84, v85
	v_cvt_pk_bf16_f32 v121, v86, v87
	v_cvt_pk_bf16_f32 v122, v88, v89
	v_cvt_pk_bf16_f32 v123, v90, v91
	v_permlane32_swap_b32_e32 v235, v252
	v_max_f32_e32 v132, v68, v69
	v_max3_f32 v132, v132, v70, v71
	s_waitcnt lgkmcnt(6)
	v_mfma_f32_32x32x16_bf16 v[2:17], v[116:119], v[146:149], v[2:17]
	ds_read_b64_tr_b16 v[146:147], v211 offset:0x3600
	ds_read_b64_tr_b16 v[148:149], v211 offset:0x3e00
	v_permlane32_swap_b32_e32 v120, v122
	v_permlane32_swap_b32_e32 v121, v123
	v_max3_f32 v132, v132, v72, v73
	v_max3_f32 v132, v132, v74, v75
	v_max3_f32 v132, v132, v76, v77
	s_waitcnt lgkmcnt(6)
	v_mfma_f32_32x32x16_bf16 v[50:65], v[120:123], v[134:137], v[50:65]
	v_max3_f32 v132, v132, v78, v79
	v_max3_f32 v132, v132, v80, v81
	v_max3_f32 v132, v132, v82, v83
	v_max3_f32 v132, v132, v100, v101
	v_max3_f32 v132, v132, v102, v103
	s_waitcnt lgkmcnt(4)
	v_mfma_f32_32x32x16_bf16 v[34:49], v[120:123], v[138:141], v[34:49]
	v_max3_f32 v132, v132, v104, v105
	v_max3_f32 v132, v132, v106, v107
	v_max3_f32 v132, v132, v108, v109
	v_max3_f32 v132, v132, v110, v111
	v_max3_f32 v132, v132, v112, v113
	v_max3_f32 v132, v132, v114, v115
	v_mov_b32_e32 v133, v132
	s_waitcnt lgkmcnt(2)
	v_mfma_f32_32x32x16_bf16 v[18:33], v[120:123], v[142:145], v[18:33]
	v_permlane32_swap_b32_e32 v132, v133
	v_max_f32_e32 v196, v132, v133
	v_cmp_ge_f32_e32 vcc, s30, v196
	s_waitcnt lgkmcnt(0)
	v_mfma_f32_32x32x16_bf16 v[2:17], v[120:123], v[146:149], v[2:17]
	s_cmp_lg_u64 vcc, exec
	s_cbranch_scc1 .LBB0_259
.LBB0_241:
	v_mov_b32_e32 v133, 1.0
	v_mov_b32_e32 v233, v234
.LBB0_243:
	s_barrier
	s_waitcnt vmcnt(3)
	v_cmp_gt_f32_e32 vcc, 1.0, v133
	s_waitcnt vmcnt(2)
	ds_write_b128 v212, v[178:181] offset:16384
	s_waitcnt vmcnt(1)
	ds_write_b128 v213, v[182:185] offset:16384
	s_waitcnt vmcnt(0)
	ds_write_b128 v229, v[186:189] offset:49152
	s_cbranch_vccnz .Lresc_h2

.Lexit_fix64:
	v_mov_b32_e32 v134, v237
	v_mov_b32_e32 v196, v237
	v_mov_b32_e32 v197, v237
	s_branch .LBB0_261
.Lcupd_f1:
	v_sub_f32_e32 v132, v133, v233
	v_mov_b32_e32 v66, v133
	v_mov_b32_e32 v236, v132
	v_mov_b32_e32 v237, v132
	v_mov_b32_e32 v238, v132
	v_mov_b32_e32 v239, v132
	v_mov_b32_e32 v240, v132
	v_mov_b32_e32 v241, v132
	v_mov_b32_e32 v242, v132
	v_mov_b32_e32 v243, v132
	v_mov_b32_e32 v244, v132
	v_mov_b32_e32 v245, v132
	v_mov_b32_e32 v246, v132
	v_mov_b32_e32 v247, v132
	v_mov_b32_e32 v248, v132
	v_mov_b32_e32 v249, v132
	v_mov_b32_e32 v250, v132
	v_mov_b32_e32 v251, v132
	s_nop 1
	s_branch .Lcret_f1

; template <bool FIRST> __device__ __forceinline__ void partialSM(f32x16& p0, f32x16& p1, float& m_reg, float& alpha, f32x16& negm, float c_cur) {
;     ...
;   if (FIRST || !__builtin_expect(__all(pmax <= THR2), 1)) {
.Ljoin_h1:
	v_cmp_ge_f32_e32 vcc, s30, v100
	s_cmp_lg_u64 vcc, exec
	s_cbranch_scc1 .LBB0_255
	s_branch .LBB0_223

; template <bool FIRST> __device__ __forceinline__ void partialSM(f32x16& p0, f32x16& p1, float& m_reg, float& alpha, f32x16& negm, float c_cur) {
;     ...
;   if (FIRST || !__builtin_expect(__all(pmax <= THR2), 1)) {
.Ljoin_h2:
	v_cmp_ge_f32_e32 vcc, s30, v196
	s_cmp_lg_u64 vcc, exec
	s_cbranch_scc1 .LBB0_259
	s_branch .LBB0_241
.Lresc_h1:
	s_and_saveexec_b64 s[4:5], s[40:41]
	ds_write_b32 v191, v232 offset:128
	s_or_b64 exec, exec, s[4:5]
	s_waitcnt lgkmcnt(0)
	v_add_u32_e32 v68, s24, v190
	ds_read_b128 v[70:73], v68 offset:128
	ds_read_b128 v[74:77], v68 offset:160
	ds_read_b128 v[78:81], v68 offset:192
	ds_read_b128 v[100:103], v68 offset:224
	s_waitcnt lgkmcnt(3)
	v_pk_mul_f32 v[34:35], v[70:71], v[34:35]
	v_pk_mul_f32 v[36:37], v[36:37], v[72:73]
	s_waitcnt lgkmcnt(2)
	v_pk_mul_f32 v[38:39], v[38:39], v[74:75]
	v_pk_mul_f32 v[40:41], v[40:41], v[76:77]
	s_waitcnt lgkmcnt(1)
	v_pk_mul_f32 v[42:43], v[42:43], v[78:79]
	v_pk_mul_f32 v[44:45], v[44:45], v[80:81]
	s_waitcnt lgkmcnt(0)
	v_pk_mul_f32 v[46:47], v[46:47], v[100:101]
	v_pk_mul_f32 v[62:63], v[62:63], v[100:101]
	v_pk_mul_f32 v[58:59], v[58:59], v[78:79]
	v_pk_mul_f32 v[54:55], v[54:55], v[74:75]
	v_pk_mul_f32 v[64:65], v[64:65], v[102:103]
	v_pk_mul_f32 v[60:61], v[60:61], v[80:81]
	v_pk_mul_f32 v[56:57], v[56:57], v[76:77]
	v_pk_mul_f32 v[52:53], v[52:53], v[72:73]
	v_pk_mul_f32 v[50:51], v[50:51], v[70:71]
	v_pk_mul_f32 v[48:49], v[48:49], v[102:103]
	v_pk_mul_f32 v[2:3], v[70:71], v[2:3]
	v_pk_mul_f32 v[4:5], v[4:5], v[72:73]
	v_pk_mul_f32 v[6:7], v[6:7], v[74:75]
	v_pk_mul_f32 v[8:9], v[8:9], v[76:77]
	v_pk_mul_f32 v[10:11], v[10:11], v[78:79]
	v_pk_mul_f32 v[12:13], v[12:13], v[80:81]
	v_pk_mul_f32 v[14:15], v[14:15], v[100:101]
	v_pk_mul_f32 v[30:31], v[30:31], v[100:101]
	v_pk_mul_f32 v[26:27], v[26:27], v[78:79]
	v_pk_mul_f32 v[22:23], v[22:23], v[74:75]
	v_pk_mul_f32 v[32:33], v[32:33], v[102:103]
	v_pk_mul_f32 v[28:29], v[28:29], v[80:81]
	v_pk_mul_f32 v[24:25], v[24:25], v[76:77]
	v_pk_mul_f32 v[20:21], v[20:21], v[72:73]
	v_pk_mul_f32 v[18:19], v[18:19], v[70:71]
	v_pk_mul_f32 v[16:17], v[16:17], v[102:103]
	s_branch .LBB0_229
.Lresc_h2:
	s_and_saveexec_b64 s[4:5], s[40:41]
	ds_write_b32 v191, v133 offset:128
	s_or_b64 exec, exec, s[4:5]
	s_waitcnt lgkmcnt(0)
	v_add_u32_e32 v98, s24, v190
	ds_read_b128 v[84:87], v98 offset:128
	ds_read_b128 v[88:91], v98 offset:160
	ds_read_b64 v[96:97], v98 offset:200
	ds_read_b128 v[92:95], v98 offset:224
	ds_read_b32 v99, v98 offset:196
	ds_read_b64 v[116:117], v98 offset:192
	s_waitcnt lgkmcnt(5)
	v_pk_mul_f32 v[2:3], v[84:85], v[2:3]
	v_pk_mul_f32 v[4:5], v[86:87], v[4:5]
	s_waitcnt lgkmcnt(4)
	v_pk_mul_f32 v[6:7], v[88:89], v[6:7]
	v_pk_mul_f32 v[8:9], v[90:91], v[8:9]
	s_waitcnt lgkmcnt(0)
	v_mov_b32_e32 v98, v116
	v_pk_mul_f32 v[60:61], v[60:61], v[96:97]
	v_pk_mul_f32 v[62:63], v[62:63], v[92:93]
	v_pk_mul_f32 v[54:55], v[54:55], v[88:89]
	v_pk_mul_f32 v[64:65], v[64:65], v[94:95]
	v_pk_mul_f32 v[58:59], v[58:59], v[98:99]
	v_pk_mul_f32 v[56:57], v[56:57], v[90:91]
	v_pk_mul_f32 v[52:53], v[52:53], v[86:87]
	v_pk_mul_f32 v[50:51], v[50:51], v[84:85]
	v_pk_mul_f32 v[44:45], v[96:97], v[44:45]
	v_pk_mul_f32 v[46:47], v[92:93], v[46:47]
	v_pk_mul_f32 v[38:39], v[88:89], v[38:39]
	v_pk_mul_f32 v[48:49], v[94:95], v[48:49]
	v_pk_mul_f32 v[42:43], v[98:99], v[42:43]
	v_pk_mul_f32 v[40:41], v[90:91], v[40:41]
	v_pk_mul_f32 v[36:37], v[86:87], v[36:37]
	v_pk_mul_f32 v[34:35], v[84:85], v[34:35]
	v_pk_mul_f32 v[28:29], v[96:97], v[28:29]
	v_pk_mul_f32 v[30:31], v[92:93], v[30:31]
	v_pk_mul_f32 v[22:23], v[88:89], v[22:23]
	v_pk_mul_f32 v[32:33], v[94:95], v[32:33]
	v_pk_mul_f32 v[26:27], v[98:99], v[26:27]
	v_pk_mul_f32 v[24:25], v[90:91], v[24:25]
	v_pk_mul_f32 v[20:21], v[86:87], v[20:21]
	v_pk_mul_f32 v[18:19], v[84:85], v[18:19]
	v_pk_mul_f32 v[10:11], v[116:117], v[10:11]
	v_pk_mul_f32 v[12:13], v[12:13], v[96:97]
	v_pk_mul_f32 v[14:15], v[14:15], v[92:93]
	v_pk_mul_f32 v[16:17], v[16:17], v[94:95]
	s_branch .LBB0_247
